# attnC: dropped redundant canonicalize before the clamp; B1 score loop: dropped in-place canonicalize before relu; attnA: relative-bias tiles read straight into the score registers with swapped ds_read
# speedup vs baseline: 1.0081x; 1.0081x over previous
.LBB0_499:
	s_andn2_b64 vcc, exec, s[14:15]
	s_cbranch_vccnz .LBB0_501
	v_add_u32_e32 v0, s22, v213
	v_add_u32_e32 v2, 0x12324, v0
	ds_read2_b32 v[48:49], v2 offset0:55 offset1:54
	ds_read2_b32 v[50:51], v2 offset0:53 offset1:52
	ds_read2_b32 v[52:53], v2 offset0:51 offset1:50
	ds_read2_b32 v[54:55], v2 offset0:49 offset1:48
	ds_read2_b32 v[56:57], v2 offset0:39 offset1:38
	ds_read2_b32 v[58:59], v2 offset0:37 offset1:36
	ds_read2_b32 v[60:61], v2 offset0:35 offset1:34
	ds_read2_b32 v[62:63], v2 offset0:33 offset1:32
	ds_read2_b32 v[64:65], v2 offset0:23 offset1:22
	ds_read2_b32 v[66:67], v2 offset0:21 offset1:20
	ds_read2_b32 v[68:69], v2 offset0:19 offset1:18
	ds_read2_b32 v[70:71], v2 offset0:17 offset1:16
	ds_read2_b32 v[72:73], v2 offset0:7 offset1:6
	ds_read2_b32 v[74:75], v2 offset0:5 offset1:4
	ds_read2_b32 v[76:77], v2 offset0:3 offset1:2
	ds_read2_b32 v[78:79], v2 offset0:1 offset1:0

.LBB0_510:
	s_andn2_b64 vcc, exec, s[14:15]
	s_cbranch_vccnz .LBB0_512
	v_add_u32_e32 v0, s22, v215
	v_add_u32_e32 v2, 0x12224, v0
	ds_read2_b32 v[48:49], v2 offset0:23 offset1:22
	ds_read2_b32 v[50:51], v2 offset0:21 offset1:20
	ds_read2_b32 v[52:53], v2 offset0:19 offset1:18
	ds_read2_b32 v[54:55], v2 offset0:17 offset1:16
	ds_read2_b32 v[56:57], v2 offset0:7 offset1:6
	ds_read2_b32 v[58:59], v2 offset0:5 offset1:4
	ds_read2_b32 v[60:61], v2 offset0:3 offset1:2
	ds_read2_b32 v[62:63], v2 offset0:1 offset1:0
	ds_read2_b32 v[64:65], v2 offset0:55 offset1:54
	ds_read2_b32 v[66:67], v2 offset0:53 offset1:52
	ds_read2_b32 v[68:69], v2 offset0:51 offset1:50
	ds_read2_b32 v[70:71], v2 offset0:49 offset1:48
	ds_read2_b32 v[72:73], v2 offset0:39 offset1:38
	ds_read2_b32 v[74:75], v2 offset0:37 offset1:36
	ds_read2_b32 v[76:77], v2 offset0:35 offset1:34
	ds_read2_b32 v[78:79], v2 offset0:33 offset1:32

; #define LAS __attribute__((address_space(3)))
; __device__ __forceinline__ int pi_row(int i) { return (i & ~12) | ((i & 4) << 1) | ((i & 8) >> 1); }
; #define MFMA32(a, b, c) __builtin_amdgcn_mfma_f32_32x32x16_bf16((a), (b), (c), 0, 0, 0)
; __device__ __forceinline__ void b1_phase(const bf16* QI, const bf16* KI, const float* WI, float* SCRb  , unsigned long long* MASK,
;                                          LAS unsigned char* lds, int vcu, int G, int tid) {
;     ...
;         for (int kt = wid; kt < ntile; kt += NWAVES) {
;             const size_t key0 = (size_t)b * SEQ + (size_t)kt * 64;
;             const bf16* kp = KI + (key0 + pi_row(r32)) * 64 + hi * 8;
;             bf16x8 kf0[4], kf1[4];
; #pragma unroll
;             for (int d0 = 0; d0 < 4; ++d0) { kf0[d0] = *(const bf16x8*)(kp + d0 * 16); kf1[d0] = *(const bf16x8*)(kp + 32 * 64 + d0 * 16); }
;             f32x16 s0 = (f32x16){}, s1 = (f32x16){};
;             int qoff = r32 * QI_PITCH + hi * 8; asm volatile("" : "+v"(qoff));
; #pragma unroll 1
;             for (int hh = 0; hh < 8; ++hh) {
;                 f32x16 a0 = (f32x16){}, a1 = (f32x16){};
;                 const float wh = wl[r32 * 8 + hh];
; #pragma unroll
;                 for (int d0 = 0; d0 < 4; ++d0) { const bf16x8 qf = *(const LAS bf16x8*)(qs + qoff + hh * 64 + d0 * 16); a0 = MFMA32(kf0[d0], qf, a0); a1 = MFMA32(kf1[d0], qf, a1); }
; #pragma unroll
;                 for (int r = 0; r < 16; ++r) { s0[r] = __builtin_fmaf(wh, __builtin_fmaxf(a0[r], 0.f), s0[r]); s1[r] = __builtin_fmaf(wh, __builtin_fmaxf(a1[r], 0.f), s1[r]); }
;             }
;             float* sp = SCRb + (size_t)r32 * 4096 + kt * 64 + 8 * hi;
; #pragma unroll
;             for (int half = 0; half < 2; ++half)
; #pragma unroll
;                 for (int s = 0; s < 2; ++s) { const f32x16& p = half ? s1 : s0;
;                     *(f32x4*)(sp + 32 * half + 16 * s) = (f32x4){p[8 * s], p[8 * s + 1], p[8 * s + 2], p[8 * s + 3]};
;                     *(f32x4*)(sp + 32 * half + 16 * s + 4) = (f32x4){p[8 * s + 4], p[8 * s + 5], p[8 * s + 6], p[8 * s + 7]}; }
.LBB0_531:
	ds_read_b128 v[18:21], v0
	ds_read_b128 v[118:121], v0 offset:32
	v_add_u32_e32 v117, s1, v116
	ds_read_b32 v122, v117
	s_add_i32 s1, s1, 4
	s_waitcnt vmcnt(7) lgkmcnt(2)
	v_mfma_f32_32x32x16_bf16 v[2:17], v[50:53], v[18:21], 0
	s_cmp_eq_u32 s1, 32
	s_waitcnt vmcnt(5)
	v_mfma_f32_32x32x16_bf16 v[18:33], v[58:61], v[18:21], 0
	s_waitcnt lgkmcnt(1)
	v_mfma_f32_32x32x16_bf16 v[2:17], v[54:57], v[118:121], v[2:17]
	s_waitcnt vmcnt(4)
	v_mfma_f32_32x32x16_bf16 v[18:33], v[62:65], v[118:121], v[18:33]
	ds_read_b128 v[118:121], v0 offset:64
	s_waitcnt vmcnt(3) lgkmcnt(0)
	v_mfma_f32_32x32x16_bf16 v[2:17], v[66:69], v[118:121], v[2:17]
	s_waitcnt vmcnt(1)
	v_mfma_f32_32x32x16_bf16 v[18:33], v[78:81], v[118:121], v[18:33]
	ds_read_b128 v[118:121], v0 offset:96
	v_add_u32_e32 v0, 0x80, v0
	s_waitcnt lgkmcnt(0)
	v_mfma_f32_32x32x16_bf16 v[2:17], v[70:73], v[118:121], v[2:17]
	s_waitcnt vmcnt(0)
	v_mfma_f32_32x32x16_bf16 v[18:33], v[82:85], v[118:121], v[18:33]
	s_nop 9
	v_max_f32_e32 v117, v4, v4
	v_max_f32_e32 v118, v5, v5
	v_max_f32_e32 v119, v6, v6
	v_max_f32_e32 v120, v7, v7
	v_max_f32_e32 v121, v8, v8
	v_max_f32_e32 v123, v9, v9
	v_max_f32_e32 v124, v10, v10
	v_max_f32_e32 v125, v11, v11
	v_max_f32_e32 v126, v12, v12
	v_max_f32_e32 v127, v13, v13
	v_max_f32_e32 v128, v14, v14
	v_max_f32_e32 v129, v15, v15
	v_max_f32_e32 v130, v16, v16
	v_max_f32_e32 v131, v17, v17
	v_max_f32_e32 v2, 0, v2
	v_max_f32_e32 v4, 0, v18
	v_max_f32_e32 v3, 0, v3
	v_max_f32_e32 v5, 0, v19
	v_max_f32_e32 v6, 0, v117
	v_max_f32_e32 v8, 0, v20
	v_max_f32_e32 v7, 0, v118
	v_max_f32_e32 v9, 0, v21
	v_max_f32_e32 v10, 0, v119
	v_max_f32_e32 v12, 0, v22
	v_max_f32_e32 v11, 0, v120
	v_max_f32_e32 v13, 0, v23
	v_max_f32_e32 v14, 0, v121
	v_max_f32_e32 v16, 0, v24
	v_max_f32_e32 v15, 0, v123
	v_max_f32_e32 v17, 0, v25
	v_max_f32_e32 v18, 0, v124
	v_max_f32_e32 v20, 0, v26
	v_max_f32_e32 v19, 0, v125
	v_max_f32_e32 v21, 0, v27
	v_max_f32_e32 v22, 0, v126
	v_max_f32_e32 v24, 0, v28
	v_max_f32_e32 v23, 0, v127
	v_max_f32_e32 v25, 0, v29
	v_max_f32_e32 v26, 0, v128
	v_max_f32_e32 v28, 0, v30
	v_max_f32_e32 v27, 0, v129
	v_max_f32_e32 v29, 0, v31
	v_max_f32_e32 v30, 0, v130
	v_max_f32_e32 v32, 0, v32
	v_max_f32_e32 v31, 0, v131
	v_max_f32_e32 v33, 0, v33
	v_pk_fma_f32 v[94:95], v[122:123], v[2:3], v[94:95] op_sel_hi:[0,1,1]
	v_pk_fma_f32 v[46:47], v[122:123], v[4:5], v[46:47] op_sel_hi:[0,1,1]
	v_pk_fma_f32 v[96:97], v[122:123], v[6:7], v[96:97] op_sel_hi:[0,1,1]
	v_pk_fma_f32 v[48:49], v[122:123], v[8:9], v[48:49] op_sel_hi:[0,1,1]
	v_pk_fma_f32 v[90:91], v[122:123], v[10:11], v[90:91] op_sel_hi:[0,1,1]
	v_pk_fma_f32 v[42:43], v[122:123], v[12:13], v[42:43] op_sel_hi:[0,1,1]
	v_pk_fma_f32 v[92:93], v[122:123], v[14:15], v[92:93] op_sel_hi:[0,1,1]
	v_pk_fma_f32 v[44:45], v[122:123], v[16:17], v[44:45] op_sel_hi:[0,1,1]
	v_pk_fma_f32 v[86:87], v[122:123], v[18:19], v[86:87] op_sel_hi:[0,1,1]
	v_pk_fma_f32 v[38:39], v[122:123], v[20:21], v[38:39] op_sel_hi:[0,1,1]
	v_pk_fma_f32 v[88:89], v[122:123], v[22:23], v[88:89] op_sel_hi:[0,1,1]
	v_pk_fma_f32 v[40:41], v[122:123], v[24:25], v[40:41] op_sel_hi:[0,1,1]
	v_pk_fma_f32 v[74:75], v[122:123], v[26:27], v[74:75] op_sel_hi:[0,1,1]
	v_pk_fma_f32 v[34:35], v[122:123], v[28:29], v[34:35] op_sel_hi:[0,1,1]
	v_pk_fma_f32 v[76:77], v[122:123], v[30:31], v[76:77] op_sel_hi:[0,1,1]
	v_pk_fma_f32 v[36:37], v[122:123], v[32:33], v[36:37] op_sel_hi:[0,1,1]
	s_cbranch_scc0 .LBB0_531
	s_lshl_b32 s4, s0, 6
	s_ashr_i32 s5, s4, 31
	s_add_i32 s0, s0, 8
	v_lshl_add_u64 v[2:3], s[4:5], 2, v[106:107]
	s_cmp_gt_i32 s0, s2
	global_store_dwordx4 v[2:3], v[94:97], off
	global_store_dwordx4 v[2:3], v[90:93], off offset:16
	global_store_dwordx4 v[2:3], v[86:89], off offset:64
	global_store_dwordx4 v[2:3], v[74:77], off offset:80
	global_store_dwordx4 v[2:3], v[46:49], off offset:128
	global_store_dwordx4 v[2:3], v[42:45], off offset:144
	global_store_dwordx4 v[2:3], v[38:41], off offset:192
	global_store_dwordx4 v[2:3], v[34:37], off offset:208
	s_cbranch_scc0 .LBB0_530

; #define LAS __attribute__((address_space(3)))
; __device__ __forceinline__ int pi_row(int i) { return (i & ~12) | ((i & 4) << 1) | ((i & 8) >> 1); }
; #define MFMA32(a, b, c) __builtin_amdgcn_mfma_f32_32x32x16_bf16((a), (b), (c), 0, 0, 0)
; template <bool INIT = true> __device__ __forceinline__ void qk_lds(f32x16& p0, f32x16& p1, const LAS unsigned char* buf, const bf16x8 (&qr)[4], int r32, int hi) {
;     const LAS unsigned char* kp = buf + pi_row(r32) * TP + hi * 16;
;     if (INIT) { p0 = (f32x16){}; p1 = (f32x16){}; }
;     bf16x8 kf[8];
; #pragma unroll
;     for (int d0 = 0; d0 < 4; ++d0) { kf[2 * d0] = *(const LAS bf16x8*)(kp + d0 * 32); kf[2 * d0 + 1] = *(const LAS bf16x8*)(kp + 32 * TP + d0 * 32); }
;     __builtin_amdgcn_s_setprio(1);
; #pragma unroll
;     for (int d0 = 0; d0 < 4; ++d0) { p0 = MFMA32(kf[2 * d0], qr[d0], p0); p1 = MFMA32(kf[2 * d0 + 1], qr[d0], p1); }
;     __builtin_amdgcn_s_setprio(0);
; }
; __device__ __forceinline__ void attnC_blk(const bf16* Q, const bf16* K, const bf16* Vt, bf16* O, LAS unsigned char* lds, int vcu, int G, int tid) {
;     ...
;                 f32x16 p0, p1; qk_lds(p0, p1, buf, qr, r32, hi);
;                 const int kb = t * 64 + 8 * hi;
;                 const bool diag = (t == t_me);
;                 float lk[32], lb[32];
; #pragma unroll
;                 for (int e = 0; e < 32; ++e) { const int r = e & 15, half = e >> 4; const float z = half ? p1[r] : p0[r];
;                     const float sp = __builtin_amdgcn_logf(1.f + __builtin_amdgcn_exp2f(fminf(z, 80.f)));
;                     lk[e] = -sp; lb[e] = z - sp; }
.LBB0_795:
	s_and_b32 s92, s90, 1
	s_mul_i32 s80, s92, 0x4800
	v_cmp_lt_i32_e32 vcc, s89, v0
	s_add_i32 s93, s80, 0
	s_or_b64 s[80:81], vcc, s[78:79]
	s_and_b64 vcc, exec, s[80:81]
	s_cbranch_vccnz .LBB0_798
	v_add3_u32 v0, s93, v107, v122
	ds_read_b128 v[2:5], v0
	ds_read_b128 v[6:9], v0 offset:32
	ds_read_b128 v[10:13], v0 offset:4608
	ds_read_b128 v[124:127], v0 offset:4640
	ds_read_b128 v[128:131], v0 offset:64
	ds_read_b128 v[132:135], v0 offset:96
	ds_read_b128 v[136:139], v0 offset:4672
	ds_read_b128 v[140:143], v0 offset:4704
	s_add_i32 s78, s91, s96
	s_setprio 1
	s_waitcnt lgkmcnt(7)
	v_mfma_f32_32x32x16_bf16 v[64:79], v[2:5], v[88:91], 0
	s_waitcnt lgkmcnt(5)
	v_mfma_f32_32x32x16_bf16 v[48:63], v[10:13], v[88:91], 0
	v_mfma_f32_32x32x16_bf16 v[64:79], v[6:9], v[92:95], v[64:79]
	s_waitcnt lgkmcnt(4)
	v_mfma_f32_32x32x16_bf16 v[48:63], v[124:127], v[92:95], v[48:63]
	s_waitcnt lgkmcnt(3)
	v_mfma_f32_32x32x16_bf16 v[64:79], v[128:131], v[96:99], v[64:79]
	s_waitcnt lgkmcnt(1)
	v_mfma_f32_32x32x16_bf16 v[48:63], v[136:139], v[96:99], v[48:63]
	v_mfma_f32_32x32x16_bf16 v[64:79], v[132:135], v[100:103], v[64:79]
	s_waitcnt lgkmcnt(0)
	v_mfma_f32_32x32x16_bf16 v[48:63], v[140:143], v[100:103], v[48:63]
	s_setprio 0
	s_nop 8
	v_min_f32_e32 v0, 0x42a00000, v64
	v_exp_f32_e32 v0, v0
	v_min_f32_e32 v2, 0x42a00000, v65
	v_exp_f32_e32 v2, v2
	v_add_f32_e32 v0, 1.0, v0
	v_log_f32_e32 v124, v0
	v_add_f32_e32 v0, 1.0, v2
	v_log_f32_e32 v115, v0
	v_min_f32_e32 v0, 0x42a00000, v66
	v_exp_f32_e32 v3, v0
	v_min_f32_e32 v4, 0x42a00000, v67
	v_exp_f32_e32 v4, v4
	v_min_f32_e32 v5, 0x42a00000, v68
	v_exp_f32_e32 v5, v5
	v_add_f32_e32 v3, 1.0, v3
	v_log_f32_e32 v127, v3
	v_add_f32_e32 v3, 1.0, v4
	v_log_f32_e32 v126, v3
	v_add_f32_e32 v3, 1.0, v5
	v_log_f32_e32 v125, v3
	v_min_f32_e32 v3, 0x42a00000, v69
	v_exp_f32_e32 v6, v3
	v_min_f32_e32 v7, 0x42a00000, v70
	v_exp_f32_e32 v7, v7
	v_min_f32_e32 v8, 0x42a00000, v71
	v_exp_f32_e32 v8, v8
	v_add_f32_e32 v6, 1.0, v6
	v_log_f32_e32 v130, v6
	v_add_f32_e32 v6, 1.0, v7
	v_log_f32_e32 v129, v6
	v_add_f32_e32 v6, 1.0, v8
	v_log_f32_e32 v128, v6
	v_min_f32_e32 v6, 0x42a00000, v72
	v_exp_f32_e32 v9, v6
	v_min_f32_e32 v10, 0x42a00000, v73
	v_exp_f32_e32 v10, v10
	v_min_f32_e32 v11, 0x42a00000, v74
	v_exp_f32_e32 v11, v11
	v_add_f32_e32 v9, 1.0, v9
	v_sub_f32_e32 v7, v70, v129
	v_log_f32_e32 v70, v9
	v_add_f32_e32 v9, 1.0, v10
	v_log_f32_e32 v132, v9
	v_add_f32_e32 v9, 1.0, v11
	v_log_f32_e32 v131, v9
	v_min_f32_e32 v9, 0x42a00000, v75
	v_exp_f32_e32 v12, v9
	v_min_f32_e32 v13, 0x42a00000, v76
	v_exp_f32_e32 v13, v13
	v_min_f32_e32 v14, 0x42a00000, v77
	v_exp_f32_e32 v14, v14
	v_add_f32_e32 v12, 1.0, v12
	v_log_f32_e32 v135, v12
	v_add_f32_e32 v12, 1.0, v13
	v_log_f32_e32 v134, v12
	v_add_f32_e32 v12, 1.0, v14
	v_log_f32_e32 v133, v12
	v_sub_f32_e32 v2, v64, v124
	v_min_f32_e32 v12, 0x42a00000, v78
	v_sub_f32_e32 v0, v65, v115
	v_exp_f32_e32 v15, v12
	v_min_f32_e32 v64, 0x42a00000, v79
	v_exp_f32_e32 v64, v64
	v_min_f32_e32 v65, 0x42a00000, v48
	v_exp_f32_e32 v65, v65
	v_add_f32_e32 v15, 1.0, v15
	v_log_f32_e32 v138, v15
	v_add_f32_e32 v15, 1.0, v64
	v_log_f32_e32 v137, v15
	v_add_f32_e32 v15, 1.0, v65
	v_log_f32_e32 v136, v15
	v_min_f32_e32 v15, 0x42a00000, v49
	v_sub_f32_e32 v5, v66, v127
	v_exp_f32_e32 v66, v15
	v_sub_f32_e32 v15, v48, v136
	v_sub_f32_e32 v4, v67, v126
	v_add_f32_e32 v48, 1.0, v66
	v_min_f32_e32 v66, 0x42a00000, v50
	v_exp_f32_e32 v66, v66
	v_min_f32_e32 v67, 0x42a00000, v51
	v_exp_f32_e32 v67, v67
	v_log_f32_e32 v141, v48
	v_add_f32_e32 v48, 1.0, v66
	v_log_f32_e32 v140, v48
	v_add_f32_e32 v48, 1.0, v67
	v_log_f32_e32 v139, v48
	v_min_f32_e32 v48, 0x42a00000, v52
	v_exp_f32_e32 v67, v48
	v_sub_f32_e32 v48, v51, v139
	v_sub_f32_e32 v66, v49, v141
	v_sub_f32_e32 v49, v50, v140
	v_add_f32_e32 v50, 1.0, v67
	v_min_f32_e32 v51, 0x42a00000, v53
	v_exp_f32_e32 v51, v51
	v_min_f32_e32 v67, 0x42a00000, v54
	v_exp_f32_e32 v67, v67
	v_log_f32_e32 v144, v50
	v_add_f32_e32 v50, 1.0, v51
	v_log_f32_e32 v143, v50
	v_add_f32_e32 v50, 1.0, v67
	v_log_f32_e32 v142, v50
	v_min_f32_e32 v50, 0x42a00000, v55
	v_exp_f32_e32 v67, v50
	v_sub_f32_e32 v50, v54, v142
	v_sub_f32_e32 v51, v53, v143
	v_add_f32_e32 v53, 1.0, v67
	v_min_f32_e32 v54, 0x42a00000, v56
	v_exp_f32_e32 v54, v54
	v_min_f32_e32 v67, 0x42a00000, v57
	v_exp_f32_e32 v67, v67
	v_log_f32_e32 v147, v53
	v_add_f32_e32 v53, 1.0, v54
	v_log_f32_e32 v146, v53
	v_add_f32_e32 v53, 1.0, v67
	v_log_f32_e32 v145, v53
	v_min_f32_e32 v53, 0x42a00000, v58
	v_exp_f32_e32 v67, v53
	v_sub_f32_e32 v53, v57, v145
	v_sub_f32_e32 v54, v56, v146
	v_add_f32_e32 v56, 1.0, v67
	v_min_f32_e32 v57, 0x42a00000, v59
	v_exp_f32_e32 v57, v57
	v_min_f32_e32 v67, 0x42a00000, v60
	v_exp_f32_e32 v67, v67
	v_log_f32_e32 v150, v56
	v_add_f32_e32 v56, 1.0, v57
	v_log_f32_e32 v149, v56
	v_add_f32_e32 v56, 1.0, v67
	v_log_f32_e32 v148, v56
	v_min_f32_e32 v56, 0x42a00000, v61
	v_exp_f32_e32 v67, v56
	v_sub_f32_e32 v56, v60, v148
	v_sub_f32_e32 v57, v59, v149
	v_add_f32_e32 v59, 1.0, v67
	v_min_f32_e32 v60, 0x42a00000, v62
	v_exp_f32_e32 v60, v60
	v_min_f32_e32 v67, 0x42a00000, v63
	v_exp_f32_e32 v67, v67
	v_log_f32_e32 v153, v59
	v_add_f32_e32 v59, 1.0, v60
	v_log_f32_e32 v152, v59
	v_add_f32_e32 v59, 1.0, v67
	v_log_f32_e32 v151, v59
	v_sub_f32_e32 v3, v68, v125
	v_sub_f32_e32 v8, v69, v130
	v_sub_f32_e32 v6, v71, v128
	v_sub_f32_e32 v11, v72, v70
	v_sub_f32_e32 v10, v73, v132
	v_sub_f32_e32 v9, v74, v131
	v_sub_f32_e32 v14, v75, v135
	v_sub_f32_e32 v13, v76, v134
	v_sub_f32_e32 v12, v77, v133
	v_sub_f32_e32 v65, v78, v138
	v_sub_f32_e32 v64, v79, v137
	v_sub_f32_e32 v52, v52, v144
	v_sub_f32_e32 v55, v55, v147
	v_sub_f32_e32 v58, v58, v150
	v_sub_f32_e32 v61, v61, v153
	v_sub_f32_e32 v59, v62, v152
	s_cmp_lg_u32 s78, -1
	v_sub_f32_e32 v60, v63, v151
	s_cbranch_scc0 .LBB0_800
; __device__ __forceinline__ void attnC_blk(const bf16* Q, const bf16* K, const bf16* Vt, bf16* O, LAS unsigned char* lds, int vcu, int G, int tid) {
;     ...
;                 for (int e = 0; e < 32; ++e) { const int r = e & 15, half = e >> 4; const float z = half ? p1[r] : p0[r];
;                     const float sp = __builtin_amdgcn_logf(1.f + __builtin_amdgcn_exp2f(fminf(z, 80.f)));
;                     lk[e] = -sp; lb[e] = z - sp; }
	v_xor_b32_e32 v62, 0x80000000, v124
	v_xor_b32_e32 v63, 0x80000000, v115
	v_xor_b32_e32 v67, 0x80000000, v127
	v_xor_b32_e32 v68, 0x80000000, v126
	v_xor_b32_e32 v69, 0x80000000, v125
	v_xor_b32_e32 v71, 0x80000000, v130
	v_xor_b32_e32 v73, 0x80000000, v129
	v_xor_b32_e32 v75, 0x80000000, v128
	v_xor_b32_e32 v70, 0x80000000, v70
	v_xor_b32_e32 v72, 0x80000000, v132
	v_xor_b32_e32 v74, 0x80000000, v131
	v_xor_b32_e32 v76, 0x80000000, v135
	v_xor_b32_e32 v77, 0x80000000, v134
	v_xor_b32_e32 v79, 0x80000000, v133
	v_xor_b32_e32 v124, 0x80000000, v138
	v_xor_b32_e32 v126, 0x80000000, v137
	v_xor_b32_e32 v78, 0x80000000, v136
	v_xor_b32_e32 v115, 0x80000000, v141
	v_xor_b32_e32 v125, 0x80000000, v140
	v_xor_b32_e32 v127, 0x80000000, v139
	v_xor_b32_e32 v129, 0x80000000, v144
	v_xor_b32_e32 v131, 0x80000000, v143
	v_xor_b32_e32 v133, 0x80000000, v142
	v_xor_b32_e32 v135, 0x80000000, v147
	v_xor_b32_e32 v128, 0x80000000, v146
	v_xor_b32_e32 v130, 0x80000000, v145
	v_xor_b32_e32 v132, 0x80000000, v150
	v_xor_b32_e32 v134, 0x80000000, v149
	v_xor_b32_e32 v136, 0x80000000, v148
	v_xor_b32_e32 v137, 0x80000000, v153
	v_xor_b32_e32 v138, 0x80000000, v152
	v_xor_b32_e32 v139, 0x80000000, v151
	s_branch .LBB0_801
